# rg_carry (phase 3 tail) rewritten: all 128 loads of a chain in one round trip instead of 8 serialized groups
# speedup vs baseline: 1.0167x; 1.0167x over previous
.LBB0_540:
	v_mov_b32_e32 v3, v204
	s_movk_i32 s1, 0x2000
	v_add_u32_e32 v2, s72, v3
	v_cmp_gt_i32_e32 vcc, s1, v2
	s_and_saveexec_b64 s[8:9], vcc
	s_cbranch_execz .LBB0_543
	s_waitcnt lgkmcnt(0)
	s_and_b32 s10, s97, 1
	s_lshl_b32 s11, s97, 17
	s_add_u32 s12, s6, 0x3400000
	s_addc_u32 s13, s7, 0
	s_add_u32 s12, s12, s11
	s_addc_u32 s13, s13, 0
	s_add_u32 s14, s6, 0x3600000
	s_addc_u32 s15, s7, 0
	s_add_u32 s14, s14, s11
	s_addc_u32 s15, s15, 0
	v_lshlrev_b32_e32 v0, 2, v204
	v_mov_b32_e32 v1, 0
	s_cmp_eq_u32 s10, 0
	s_cbranch_scc0 .Lrgc_rev
	s_add_u32 s16, s12, 0x1000
	s_addc_u32 s17, s13, 0
	s_add_u32 s18, s14, 0x1000
	s_addc_u32 s19, s15, 0
	global_load_dword v32, v0, s[16:17] offset:-4096
	global_load_dword v96, v0, s[18:19] offset:-4096
	global_load_dword v33, v0, s[16:17] offset:-2048
	global_load_dword v97, v0, s[18:19] offset:-2048
	global_load_dword v34, v0, s[16:17] offset:0
	global_load_dword v98, v0, s[18:19] offset:0
	global_load_dword v35, v0, s[16:17] offset:2048
	global_load_dword v99, v0, s[18:19] offset:2048
	s_add_u32 s16, s12, 0x3000
	s_addc_u32 s17, s13, 0
	s_add_u32 s18, s14, 0x3000
	s_addc_u32 s19, s15, 0
	global_load_dword v36, v0, s[16:17] offset:-4096
	global_load_dword v100, v0, s[18:19] offset:-4096
	global_load_dword v37, v0, s[16:17] offset:-2048
	global_load_dword v101, v0, s[18:19] offset:-2048
	global_load_dword v38, v0, s[16:17] offset:0
	global_load_dword v102, v0, s[18:19] offset:0
	global_load_dword v39, v0, s[16:17] offset:2048
	global_load_dword v103, v0, s[18:19] offset:2048
	s_add_u32 s16, s12, 0x5000
	s_addc_u32 s17, s13, 0
	s_add_u32 s18, s14, 0x5000
	s_addc_u32 s19, s15, 0
	global_load_dword v40, v0, s[16:17] offset:-4096
	global_load_dword v104, v0, s[18:19] offset:-4096
	global_load_dword v41, v0, s[16:17] offset:-2048
	global_load_dword v105, v0, s[18:19] offset:-2048
	global_load_dword v42, v0, s[16:17] offset:0
	global_load_dword v106, v0, s[18:19] offset:0
	global_load_dword v43, v0, s[16:17] offset:2048
	global_load_dword v107, v0, s[18:19] offset:2048
	s_add_u32 s16, s12, 0x7000
	s_addc_u32 s17, s13, 0
	s_add_u32 s18, s14, 0x7000
	s_addc_u32 s19, s15, 0
	global_load_dword v44, v0, s[16:17] offset:-4096
	global_load_dword v108, v0, s[18:19] offset:-4096
	global_load_dword v45, v0, s[16:17] offset:-2048
	global_load_dword v109, v0, s[18:19] offset:-2048
	global_load_dword v46, v0, s[16:17] offset:0
	global_load_dword v110, v0, s[18:19] offset:0
	global_load_dword v47, v0, s[16:17] offset:2048
	global_load_dword v111, v0, s[18:19] offset:2048
	s_add_u32 s16, s12, 0x9000
	s_addc_u32 s17, s13, 0
	s_add_u32 s18, s14, 0x9000
	s_addc_u32 s19, s15, 0
	global_load_dword v48, v0, s[16:17] offset:-4096
	global_load_dword v112, v0, s[18:19] offset:-4096
	global_load_dword v49, v0, s[16:17] offset:-2048
	global_load_dword v113, v0, s[18:19] offset:-2048
	global_load_dword v50, v0, s[16:17] offset:0
	global_load_dword v114, v0, s[18:19] offset:0
	global_load_dword v51, v0, s[16:17] offset:2048
	global_load_dword v115, v0, s[18:19] offset:2048
	s_add_u32 s16, s12, 0xb000
	s_addc_u32 s17, s13, 0
	s_add_u32 s18, s14, 0xb000
	s_addc_u32 s19, s15, 0
	global_load_dword v52, v0, s[16:17] offset:-4096
	global_load_dword v116, v0, s[18:19] offset:-4096
	global_load_dword v53, v0, s[16:17] offset:-2048
	global_load_dword v117, v0, s[18:19] offset:-2048
	global_load_dword v54, v0, s[16:17] offset:0
	global_load_dword v118, v0, s[18:19] offset:0
	global_load_dword v55, v0, s[16:17] offset:2048
	global_load_dword v119, v0, s[18:19] offset:2048
	s_add_u32 s16, s12, 0xd000
	s_addc_u32 s17, s13, 0
	s_add_u32 s18, s14, 0xd000
	s_addc_u32 s19, s15, 0
	global_load_dword v56, v0, s[16:17] offset:-4096
	global_load_dword v120, v0, s[18:19] offset:-4096
	global_load_dword v57, v0, s[16:17] offset:-2048
	global_load_dword v121, v0, s[18:19] offset:-2048
	global_load_dword v58, v0, s[16:17] offset:0
	global_load_dword v122, v0, s[18:19] offset:0
	global_load_dword v59, v0, s[16:17] offset:2048
	global_load_dword v123, v0, s[18:19] offset:2048
	s_add_u32 s16, s12, 0xf000
	s_addc_u32 s17, s13, 0
	s_add_u32 s18, s14, 0xf000
	s_addc_u32 s19, s15, 0
	global_load_dword v60, v0, s[16:17] offset:-4096
	global_load_dword v124, v0, s[18:19] offset:-4096
	global_load_dword v61, v0, s[16:17] offset:-2048
	global_load_dword v125, v0, s[18:19] offset:-2048
	global_load_dword v62, v0, s[16:17] offset:0
	global_load_dword v126, v0, s[18:19] offset:0
	global_load_dword v63, v0, s[16:17] offset:2048
	global_load_dword v127, v0, s[18:19] offset:2048
	s_add_u32 s16, s12, 0x11000
	s_addc_u32 s17, s13, 0
	s_add_u32 s18, s14, 0x11000
	s_addc_u32 s19, s15, 0
	global_load_dword v64, v0, s[16:17] offset:-4096
	global_load_dword v128, v0, s[18:19] offset:-4096
	global_load_dword v65, v0, s[16:17] offset:-2048
	global_load_dword v129, v0, s[18:19] offset:-2048
	global_load_dword v66, v0, s[16:17] offset:0
	global_load_dword v130, v0, s[18:19] offset:0
	global_load_dword v67, v0, s[16:17] offset:2048
	global_load_dword v131, v0, s[18:19] offset:2048
	s_add_u32 s16, s12, 0x13000
	s_addc_u32 s17, s13, 0
	s_add_u32 s18, s14, 0x13000
	s_addc_u32 s19, s15, 0
	global_load_dword v68, v0, s[16:17] offset:-4096
	global_load_dword v132, v0, s[18:19] offset:-4096
	global_load_dword v69, v0, s[16:17] offset:-2048
	global_load_dword v133, v0, s[18:19] offset:-2048
	global_load_dword v70, v0, s[16:17] offset:0
	global_load_dword v134, v0, s[18:19] offset:0
	global_load_dword v71, v0, s[16:17] offset:2048
	global_load_dword v135, v0, s[18:19] offset:2048
	s_add_u32 s16, s12, 0x15000
	s_addc_u32 s17, s13, 0
	s_add_u32 s18, s14, 0x15000
	s_addc_u32 s19, s15, 0
	global_load_dword v72, v0, s[16:17] offset:-4096
	global_load_dword v136, v0, s[18:19] offset:-4096
	global_load_dword v73, v0, s[16:17] offset:-2048
	global_load_dword v137, v0, s[18:19] offset:-2048
	global_load_dword v74, v0, s[16:17] offset:0
	global_load_dword v138, v0, s[18:19] offset:0
	global_load_dword v75, v0, s[16:17] offset:2048
	global_load_dword v139, v0, s[18:19] offset:2048
	s_add_u32 s16, s12, 0x17000
	s_addc_u32 s17, s13, 0
	s_add_u32 s18, s14, 0x17000
	s_addc_u32 s19, s15, 0
	global_load_dword v76, v0, s[16:17] offset:-4096
	global_load_dword v140, v0, s[18:19] offset:-4096
	global_load_dword v77, v0, s[16:17] offset:-2048
	global_load_dword v141, v0, s[18:19] offset:-2048
	global_load_dword v78, v0, s[16:17] offset:0
	global_load_dword v142, v0, s[18:19] offset:0
	global_load_dword v79, v0, s[16:17] offset:2048
	global_load_dword v143, v0, s[18:19] offset:2048
	s_add_u32 s16, s12, 0x19000
	s_addc_u32 s17, s13, 0
	s_add_u32 s18, s14, 0x19000
	s_addc_u32 s19, s15, 0
	global_load_dword v80, v0, s[16:17] offset:-4096
	global_load_dword v144, v0, s[18:19] offset:-4096
	global_load_dword v81, v0, s[16:17] offset:-2048
	global_load_dword v145, v0, s[18:19] offset:-2048
	global_load_dword v82, v0, s[16:17] offset:0
	global_load_dword v146, v0, s[18:19] offset:0
	global_load_dword v83, v0, s[16:17] offset:2048
	global_load_dword v147, v0, s[18:19] offset:2048
	s_add_u32 s16, s12, 0x1b000
	s_addc_u32 s17, s13, 0
	s_add_u32 s18, s14, 0x1b000
	s_addc_u32 s19, s15, 0
	global_load_dword v84, v0, s[16:17] offset:-4096
	global_load_dword v148, v0, s[18:19] offset:-4096
	global_load_dword v85, v0, s[16:17] offset:-2048
	global_load_dword v149, v0, s[18:19] offset:-2048
	global_load_dword v86, v0, s[16:17] offset:0
	global_load_dword v150, v0, s[18:19] offset:0
	global_load_dword v87, v0, s[16:17] offset:2048
	global_load_dword v151, v0, s[18:19] offset:2048
	s_add_u32 s16, s12, 0x1d000
	s_addc_u32 s17, s13, 0
	s_add_u32 s18, s14, 0x1d000
	s_addc_u32 s19, s15, 0
	global_load_dword v88, v0, s[16:17] offset:-4096
	global_load_dword v153, v0, s[18:19] offset:-4096
	global_load_dword v89, v0, s[16:17] offset:-2048
	global_load_dword v154, v0, s[18:19] offset:-2048
	global_load_dword v90, v0, s[16:17] offset:0
	global_load_dword v155, v0, s[18:19] offset:0
	global_load_dword v91, v0, s[16:17] offset:2048
	global_load_dword v156, v0, s[18:19] offset:2048
	s_add_u32 s16, s12, 0x1f000
	s_addc_u32 s17, s13, 0
	s_add_u32 s18, s14, 0x1f000
	s_addc_u32 s19, s15, 0
	global_load_dword v92, v0, s[16:17] offset:-4096
	global_load_dword v157, v0, s[18:19] offset:-4096
	global_load_dword v93, v0, s[16:17] offset:-2048
	global_load_dword v158, v0, s[18:19] offset:-2048
	global_load_dword v94, v0, s[16:17] offset:0
	global_load_dword v159, v0, s[18:19] offset:0
	global_load_dword v95, v0, s[16:17] offset:2048
	global_load_dword v160, v0, s[18:19] offset:2048
	s_waitcnt vmcnt(0)
	s_add_u32 s18, s14, 0x1000
	s_addc_u32 s19, s15, 0
	global_store_dword v0, v1, s[18:19] offset:-4096
	v_fmac_f32_e32 v96, v1, v32
	global_store_dword v0, v96, s[18:19] offset:-2048
	v_fmac_f32_e32 v97, v96, v33
	global_store_dword v0, v97, s[18:19] offset:0
	v_fmac_f32_e32 v98, v97, v34
	global_store_dword v0, v98, s[18:19] offset:2048
	v_fmac_f32_e32 v99, v98, v35
	s_add_u32 s18, s14, 0x3000
	s_addc_u32 s19, s15, 0
	global_store_dword v0, v99, s[18:19] offset:-4096
	v_fmac_f32_e32 v100, v99, v36
	global_store_dword v0, v100, s[18:19] offset:-2048
	v_fmac_f32_e32 v101, v100, v37
	global_store_dword v0, v101, s[18:19] offset:0
	v_fmac_f32_e32 v102, v101, v38
	global_store_dword v0, v102, s[18:19] offset:2048
	v_fmac_f32_e32 v103, v102, v39
	s_add_u32 s18, s14, 0x5000
	s_addc_u32 s19, s15, 0
	global_store_dword v0, v103, s[18:19] offset:-4096
	v_fmac_f32_e32 v104, v103, v40
	global_store_dword v0, v104, s[18:19] offset:-2048
	v_fmac_f32_e32 v105, v104, v41
	global_store_dword v0, v105, s[18:19] offset:0
	v_fmac_f32_e32 v106, v105, v42
	global_store_dword v0, v106, s[18:19] offset:2048
	v_fmac_f32_e32 v107, v106, v43
	s_add_u32 s18, s14, 0x7000
	s_addc_u32 s19, s15, 0
	global_store_dword v0, v107, s[18:19] offset:-4096
	v_fmac_f32_e32 v108, v107, v44
	global_store_dword v0, v108, s[18:19] offset:-2048
	v_fmac_f32_e32 v109, v108, v45
	global_store_dword v0, v109, s[18:19] offset:0
	v_fmac_f32_e32 v110, v109, v46
	global_store_dword v0, v110, s[18:19] offset:2048
	v_fmac_f32_e32 v111, v110, v47
	s_add_u32 s18, s14, 0x9000
	s_addc_u32 s19, s15, 0
	global_store_dword v0, v111, s[18:19] offset:-4096
	v_fmac_f32_e32 v112, v111, v48
	global_store_dword v0, v112, s[18:19] offset:-2048
	v_fmac_f32_e32 v113, v112, v49
	global_store_dword v0, v113, s[18:19] offset:0
	v_fmac_f32_e32 v114, v113, v50
	global_store_dword v0, v114, s[18:19] offset:2048
	v_fmac_f32_e32 v115, v114, v51
	s_add_u32 s18, s14, 0xb000
	s_addc_u32 s19, s15, 0
	global_store_dword v0, v115, s[18:19] offset:-4096
	v_fmac_f32_e32 v116, v115, v52
	global_store_dword v0, v116, s[18:19] offset:-2048
	v_fmac_f32_e32 v117, v116, v53
	global_store_dword v0, v117, s[18:19] offset:0
	v_fmac_f32_e32 v118, v117, v54
	global_store_dword v0, v118, s[18:19] offset:2048
	v_fmac_f32_e32 v119, v118, v55
	s_add_u32 s18, s14, 0xd000
	s_addc_u32 s19, s15, 0
	global_store_dword v0, v119, s[18:19] offset:-4096
	v_fmac_f32_e32 v120, v119, v56
	global_store_dword v0, v120, s[18:19] offset:-2048
	v_fmac_f32_e32 v121, v120, v57
	global_store_dword v0, v121, s[18:19] offset:0
	v_fmac_f32_e32 v122, v121, v58
	global_store_dword v0, v122, s[18:19] offset:2048
	v_fmac_f32_e32 v123, v122, v59
	s_add_u32 s18, s14, 0xf000
	s_addc_u32 s19, s15, 0
	global_store_dword v0, v123, s[18:19] offset:-4096
	v_fmac_f32_e32 v124, v123, v60
	global_store_dword v0, v124, s[18:19] offset:-2048
	v_fmac_f32_e32 v125, v124, v61
	global_store_dword v0, v125, s[18:19] offset:0
	v_fmac_f32_e32 v126, v125, v62
	global_store_dword v0, v126, s[18:19] offset:2048
	v_fmac_f32_e32 v127, v126, v63
	s_add_u32 s18, s14, 0x11000
	s_addc_u32 s19, s15, 0
	global_store_dword v0, v127, s[18:19] offset:-4096
	v_fmac_f32_e32 v128, v127, v64
	global_store_dword v0, v128, s[18:19] offset:-2048
	v_fmac_f32_e32 v129, v128, v65
	global_store_dword v0, v129, s[18:19] offset:0
	v_fmac_f32_e32 v130, v129, v66
	global_store_dword v0, v130, s[18:19] offset:2048
	v_fmac_f32_e32 v131, v130, v67
	s_add_u32 s18, s14, 0x13000
	s_addc_u32 s19, s15, 0
	global_store_dword v0, v131, s[18:19] offset:-4096
	v_fmac_f32_e32 v132, v131, v68
	global_store_dword v0, v132, s[18:19] offset:-2048
	v_fmac_f32_e32 v133, v132, v69
	global_store_dword v0, v133, s[18:19] offset:0
	v_fmac_f32_e32 v134, v133, v70
	global_store_dword v0, v134, s[18:19] offset:2048
	v_fmac_f32_e32 v135, v134, v71
	s_add_u32 s18, s14, 0x15000
	s_addc_u32 s19, s15, 0
	global_store_dword v0, v135, s[18:19] offset:-4096
	v_fmac_f32_e32 v136, v135, v72
	global_store_dword v0, v136, s[18:19] offset:-2048
	v_fmac_f32_e32 v137, v136, v73
	global_store_dword v0, v137, s[18:19] offset:0
	v_fmac_f32_e32 v138, v137, v74
	global_store_dword v0, v138, s[18:19] offset:2048
	v_fmac_f32_e32 v139, v138, v75
	s_add_u32 s18, s14, 0x17000
	s_addc_u32 s19, s15, 0
	global_store_dword v0, v139, s[18:19] offset:-4096
	v_fmac_f32_e32 v140, v139, v76
	global_store_dword v0, v140, s[18:19] offset:-2048
	v_fmac_f32_e32 v141, v140, v77
	global_store_dword v0, v141, s[18:19] offset:0
	v_fmac_f32_e32 v142, v141, v78
	global_store_dword v0, v142, s[18:19] offset:2048
	v_fmac_f32_e32 v143, v142, v79
	s_add_u32 s18, s14, 0x19000
	s_addc_u32 s19, s15, 0
	global_store_dword v0, v143, s[18:19] offset:-4096
	v_fmac_f32_e32 v144, v143, v80
	global_store_dword v0, v144, s[18:19] offset:-2048
	v_fmac_f32_e32 v145, v144, v81
	global_store_dword v0, v145, s[18:19] offset:0
	v_fmac_f32_e32 v146, v145, v82
	global_store_dword v0, v146, s[18:19] offset:2048
	v_fmac_f32_e32 v147, v146, v83
	s_add_u32 s18, s14, 0x1b000
	s_addc_u32 s19, s15, 0
	global_store_dword v0, v147, s[18:19] offset:-4096
	v_fmac_f32_e32 v148, v147, v84
	global_store_dword v0, v148, s[18:19] offset:-2048
	v_fmac_f32_e32 v149, v148, v85
	global_store_dword v0, v149, s[18:19] offset:0
	v_fmac_f32_e32 v150, v149, v86
	global_store_dword v0, v150, s[18:19] offset:2048
	v_fmac_f32_e32 v151, v150, v87
	s_add_u32 s18, s14, 0x1d000
	s_addc_u32 s19, s15, 0
	global_store_dword v0, v151, s[18:19] offset:-4096
	v_fmac_f32_e32 v153, v151, v88
	global_store_dword v0, v153, s[18:19] offset:-2048
	v_fmac_f32_e32 v154, v153, v89
	global_store_dword v0, v154, s[18:19] offset:0
	v_fmac_f32_e32 v155, v154, v90
	global_store_dword v0, v155, s[18:19] offset:2048
	v_fmac_f32_e32 v156, v155, v91
	s_add_u32 s18, s14, 0x1f000
	s_addc_u32 s19, s15, 0
	global_store_dword v0, v156, s[18:19] offset:-4096
	v_fmac_f32_e32 v157, v156, v92
	global_store_dword v0, v157, s[18:19] offset:-2048
	v_fmac_f32_e32 v158, v157, v93
	global_store_dword v0, v158, s[18:19] offset:0
	v_fmac_f32_e32 v159, v158, v94
	global_store_dword v0, v159, s[18:19] offset:2048
	v_fmac_f32_e32 v160, v159, v95
	s_branch .LBB0_543
.Lrgc_rev:
	s_add_u32 s16, s12, 0x1f000
	s_addc_u32 s17, s13, 0
	s_add_u32 s18, s14, 0x1f000
	s_addc_u32 s19, s15, 0
	global_load_dword v32, v0, s[16:17] offset:2048
	global_load_dword v96, v0, s[18:19] offset:2048
	global_load_dword v33, v0, s[16:17] offset:0
	global_load_dword v97, v0, s[18:19] offset:0
	global_load_dword v34, v0, s[16:17] offset:-2048
	global_load_dword v98, v0, s[18:19] offset:-2048
	global_load_dword v35, v0, s[16:17] offset:-4096
	global_load_dword v99, v0, s[18:19] offset:-4096
	s_add_u32 s16, s12, 0x1d000
	s_addc_u32 s17, s13, 0
	s_add_u32 s18, s14, 0x1d000
	s_addc_u32 s19, s15, 0
	global_load_dword v36, v0, s[16:17] offset:2048
	global_load_dword v100, v0, s[18:19] offset:2048
	global_load_dword v37, v0, s[16:17] offset:0
	global_load_dword v101, v0, s[18:19] offset:0
	global_load_dword v38, v0, s[16:17] offset:-2048
	global_load_dword v102, v0, s[18:19] offset:-2048
	global_load_dword v39, v0, s[16:17] offset:-4096
	global_load_dword v103, v0, s[18:19] offset:-4096
	s_add_u32 s16, s12, 0x1b000
	s_addc_u32 s17, s13, 0
	s_add_u32 s18, s14, 0x1b000
	s_addc_u32 s19, s15, 0
	global_load_dword v40, v0, s[16:17] offset:2048
	global_load_dword v104, v0, s[18:19] offset:2048
	global_load_dword v41, v0, s[16:17] offset:0
	global_load_dword v105, v0, s[18:19] offset:0
	global_load_dword v42, v0, s[16:17] offset:-2048
	global_load_dword v106, v0, s[18:19] offset:-2048
	global_load_dword v43, v0, s[16:17] offset:-4096
	global_load_dword v107, v0, s[18:19] offset:-4096
	s_add_u32 s16, s12, 0x19000
	s_addc_u32 s17, s13, 0
	s_add_u32 s18, s14, 0x19000
	s_addc_u32 s19, s15, 0
	global_load_dword v44, v0, s[16:17] offset:2048
	global_load_dword v108, v0, s[18:19] offset:2048
	global_load_dword v45, v0, s[16:17] offset:0
	global_load_dword v109, v0, s[18:19] offset:0
	global_load_dword v46, v0, s[16:17] offset:-2048
	global_load_dword v110, v0, s[18:19] offset:-2048
	global_load_dword v47, v0, s[16:17] offset:-4096
	global_load_dword v111, v0, s[18:19] offset:-4096
	s_add_u32 s16, s12, 0x17000
	s_addc_u32 s17, s13, 0
	s_add_u32 s18, s14, 0x17000
	s_addc_u32 s19, s15, 0
	global_load_dword v48, v0, s[16:17] offset:2048
	global_load_dword v112, v0, s[18:19] offset:2048
	global_load_dword v49, v0, s[16:17] offset:0
	global_load_dword v113, v0, s[18:19] offset:0
	global_load_dword v50, v0, s[16:17] offset:-2048
	global_load_dword v114, v0, s[18:19] offset:-2048
	global_load_dword v51, v0, s[16:17] offset:-4096
	global_load_dword v115, v0, s[18:19] offset:-4096
	s_add_u32 s16, s12, 0x15000
	s_addc_u32 s17, s13, 0
	s_add_u32 s18, s14, 0x15000
	s_addc_u32 s19, s15, 0
	global_load_dword v52, v0, s[16:17] offset:2048
	global_load_dword v116, v0, s[18:19] offset:2048
	global_load_dword v53, v0, s[16:17] offset:0
	global_load_dword v117, v0, s[18:19] offset:0
	global_load_dword v54, v0, s[16:17] offset:-2048
	global_load_dword v118, v0, s[18:19] offset:-2048
	global_load_dword v55, v0, s[16:17] offset:-4096
	global_load_dword v119, v0, s[18:19] offset:-4096
	s_add_u32 s16, s12, 0x13000
	s_addc_u32 s17, s13, 0
	s_add_u32 s18, s14, 0x13000
	s_addc_u32 s19, s15, 0
	global_load_dword v56, v0, s[16:17] offset:2048
	global_load_dword v120, v0, s[18:19] offset:2048
	global_load_dword v57, v0, s[16:17] offset:0
	global_load_dword v121, v0, s[18:19] offset:0
	global_load_dword v58, v0, s[16:17] offset:-2048
	global_load_dword v122, v0, s[18:19] offset:-2048
	global_load_dword v59, v0, s[16:17] offset:-4096
	global_load_dword v123, v0, s[18:19] offset:-4096
	s_add_u32 s16, s12, 0x11000
	s_addc_u32 s17, s13, 0
	s_add_u32 s18, s14, 0x11000
	s_addc_u32 s19, s15, 0
	global_load_dword v60, v0, s[16:17] offset:2048
	global_load_dword v124, v0, s[18:19] offset:2048
	global_load_dword v61, v0, s[16:17] offset:0
	global_load_dword v125, v0, s[18:19] offset:0
	global_load_dword v62, v0, s[16:17] offset:-2048
	global_load_dword v126, v0, s[18:19] offset:-2048
	global_load_dword v63, v0, s[16:17] offset:-4096
	global_load_dword v127, v0, s[18:19] offset:-4096
	s_add_u32 s16, s12, 0xf000
	s_addc_u32 s17, s13, 0
	s_add_u32 s18, s14, 0xf000
	s_addc_u32 s19, s15, 0
	global_load_dword v64, v0, s[16:17] offset:2048
	global_load_dword v128, v0, s[18:19] offset:2048
	global_load_dword v65, v0, s[16:17] offset:0
	global_load_dword v129, v0, s[18:19] offset:0
	global_load_dword v66, v0, s[16:17] offset:-2048
	global_load_dword v130, v0, s[18:19] offset:-2048
	global_load_dword v67, v0, s[16:17] offset:-4096
	global_load_dword v131, v0, s[18:19] offset:-4096
	s_add_u32 s16, s12, 0xd000
	s_addc_u32 s17, s13, 0
	s_add_u32 s18, s14, 0xd000
	s_addc_u32 s19, s15, 0
	global_load_dword v68, v0, s[16:17] offset:2048
	global_load_dword v132, v0, s[18:19] offset:2048
	global_load_dword v69, v0, s[16:17] offset:0
	global_load_dword v133, v0, s[18:19] offset:0
	global_load_dword v70, v0, s[16:17] offset:-2048
	global_load_dword v134, v0, s[18:19] offset:-2048
	global_load_dword v71, v0, s[16:17] offset:-4096
	global_load_dword v135, v0, s[18:19] offset:-4096
	s_add_u32 s16, s12, 0xb000
	s_addc_u32 s17, s13, 0
	s_add_u32 s18, s14, 0xb000
	s_addc_u32 s19, s15, 0
	global_load_dword v72, v0, s[16:17] offset:2048
	global_load_dword v136, v0, s[18:19] offset:2048
	global_load_dword v73, v0, s[16:17] offset:0
	global_load_dword v137, v0, s[18:19] offset:0
	global_load_dword v74, v0, s[16:17] offset:-2048
	global_load_dword v138, v0, s[18:19] offset:-2048
	global_load_dword v75, v0, s[16:17] offset:-4096
	global_load_dword v139, v0, s[18:19] offset:-4096
	s_add_u32 s16, s12, 0x9000
	s_addc_u32 s17, s13, 0
	s_add_u32 s18, s14, 0x9000
	s_addc_u32 s19, s15, 0
	global_load_dword v76, v0, s[16:17] offset:2048
	global_load_dword v140, v0, s[18:19] offset:2048
	global_load_dword v77, v0, s[16:17] offset:0
	global_load_dword v141, v0, s[18:19] offset:0
	global_load_dword v78, v0, s[16:17] offset:-2048
	global_load_dword v142, v0, s[18:19] offset:-2048
	global_load_dword v79, v0, s[16:17] offset:-4096
	global_load_dword v143, v0, s[18:19] offset:-4096
	s_add_u32 s16, s12, 0x7000
	s_addc_u32 s17, s13, 0
	s_add_u32 s18, s14, 0x7000
	s_addc_u32 s19, s15, 0
	global_load_dword v80, v0, s[16:17] offset:2048
	global_load_dword v144, v0, s[18:19] offset:2048
	global_load_dword v81, v0, s[16:17] offset:0
	global_load_dword v145, v0, s[18:19] offset:0
	global_load_dword v82, v0, s[16:17] offset:-2048
	global_load_dword v146, v0, s[18:19] offset:-2048
	global_load_dword v83, v0, s[16:17] offset:-4096
	global_load_dword v147, v0, s[18:19] offset:-4096
	s_add_u32 s16, s12, 0x5000
	s_addc_u32 s17, s13, 0
	s_add_u32 s18, s14, 0x5000
	s_addc_u32 s19, s15, 0
	global_load_dword v84, v0, s[16:17] offset:2048
	global_load_dword v148, v0, s[18:19] offset:2048
	global_load_dword v85, v0, s[16:17] offset:0
	global_load_dword v149, v0, s[18:19] offset:0
	global_load_dword v86, v0, s[16:17] offset:-2048
	global_load_dword v150, v0, s[18:19] offset:-2048
	global_load_dword v87, v0, s[16:17] offset:-4096
	global_load_dword v151, v0, s[18:19] offset:-4096
	s_add_u32 s16, s12, 0x3000
	s_addc_u32 s17, s13, 0
	s_add_u32 s18, s14, 0x3000
	s_addc_u32 s19, s15, 0
	global_load_dword v88, v0, s[16:17] offset:2048
	global_load_dword v153, v0, s[18:19] offset:2048
	global_load_dword v89, v0, s[16:17] offset:0
	global_load_dword v154, v0, s[18:19] offset:0
	global_load_dword v90, v0, s[16:17] offset:-2048
	global_load_dword v155, v0, s[18:19] offset:-2048
	global_load_dword v91, v0, s[16:17] offset:-4096
	global_load_dword v156, v0, s[18:19] offset:-4096
	s_add_u32 s16, s12, 0x1000
	s_addc_u32 s17, s13, 0
	s_add_u32 s18, s14, 0x1000
	s_addc_u32 s19, s15, 0
	global_load_dword v92, v0, s[16:17] offset:2048
	global_load_dword v157, v0, s[18:19] offset:2048
	global_load_dword v93, v0, s[16:17] offset:0
	global_load_dword v158, v0, s[18:19] offset:0
	global_load_dword v94, v0, s[16:17] offset:-2048
	global_load_dword v159, v0, s[18:19] offset:-2048
	global_load_dword v95, v0, s[16:17] offset:-4096
	global_load_dword v160, v0, s[18:19] offset:-4096
	s_waitcnt vmcnt(0)
	s_add_u32 s18, s14, 0x1f000
	s_addc_u32 s19, s15, 0
	global_store_dword v0, v1, s[18:19] offset:2048
	v_fmac_f32_e32 v96, v1, v32
	global_store_dword v0, v96, s[18:19] offset:0
	v_fmac_f32_e32 v97, v96, v33
	global_store_dword v0, v97, s[18:19] offset:-2048
	v_fmac_f32_e32 v98, v97, v34
	global_store_dword v0, v98, s[18:19] offset:-4096
	v_fmac_f32_e32 v99, v98, v35
	s_add_u32 s18, s14, 0x1d000
	s_addc_u32 s19, s15, 0
	global_store_dword v0, v99, s[18:19] offset:2048
	v_fmac_f32_e32 v100, v99, v36
	global_store_dword v0, v100, s[18:19] offset:0
	v_fmac_f32_e32 v101, v100, v37
	global_store_dword v0, v101, s[18:19] offset:-2048
	v_fmac_f32_e32 v102, v101, v38
	global_store_dword v0, v102, s[18:19] offset:-4096
	v_fmac_f32_e32 v103, v102, v39
	s_add_u32 s18, s14, 0x1b000
	s_addc_u32 s19, s15, 0
	global_store_dword v0, v103, s[18:19] offset:2048
	v_fmac_f32_e32 v104, v103, v40
	global_store_dword v0, v104, s[18:19] offset:0
	v_fmac_f32_e32 v105, v104, v41
	global_store_dword v0, v105, s[18:19] offset:-2048
	v_fmac_f32_e32 v106, v105, v42
	global_store_dword v0, v106, s[18:19] offset:-4096
	v_fmac_f32_e32 v107, v106, v43
	s_add_u32 s18, s14, 0x19000
	s_addc_u32 s19, s15, 0
	global_store_dword v0, v107, s[18:19] offset:2048
	v_fmac_f32_e32 v108, v107, v44
	global_store_dword v0, v108, s[18:19] offset:0
	v_fmac_f32_e32 v109, v108, v45
	global_store_dword v0, v109, s[18:19] offset:-2048
	v_fmac_f32_e32 v110, v109, v46
	global_store_dword v0, v110, s[18:19] offset:-4096
	v_fmac_f32_e32 v111, v110, v47
	s_add_u32 s18, s14, 0x17000
	s_addc_u32 s19, s15, 0
	global_store_dword v0, v111, s[18:19] offset:2048
	v_fmac_f32_e32 v112, v111, v48
	global_store_dword v0, v112, s[18:19] offset:0
	v_fmac_f32_e32 v113, v112, v49
	global_store_dword v0, v113, s[18:19] offset:-2048
	v_fmac_f32_e32 v114, v113, v50
	global_store_dword v0, v114, s[18:19] offset:-4096
	v_fmac_f32_e32 v115, v114, v51
	s_add_u32 s18, s14, 0x15000
	s_addc_u32 s19, s15, 0
	global_store_dword v0, v115, s[18:19] offset:2048
	v_fmac_f32_e32 v116, v115, v52
	global_store_dword v0, v116, s[18:19] offset:0
	v_fmac_f32_e32 v117, v116, v53
	global_store_dword v0, v117, s[18:19] offset:-2048
	v_fmac_f32_e32 v118, v117, v54
	global_store_dword v0, v118, s[18:19] offset:-4096
	v_fmac_f32_e32 v119, v118, v55
	s_add_u32 s18, s14, 0x13000
	s_addc_u32 s19, s15, 0
	global_store_dword v0, v119, s[18:19] offset:2048
	v_fmac_f32_e32 v120, v119, v56
	global_store_dword v0, v120, s[18:19] offset:0
	v_fmac_f32_e32 v121, v120, v57
	global_store_dword v0, v121, s[18:19] offset:-2048
	v_fmac_f32_e32 v122, v121, v58
	global_store_dword v0, v122, s[18:19] offset:-4096
	v_fmac_f32_e32 v123, v122, v59
	s_add_u32 s18, s14, 0x11000
	s_addc_u32 s19, s15, 0
	global_store_dword v0, v123, s[18:19] offset:2048
	v_fmac_f32_e32 v124, v123, v60
	global_store_dword v0, v124, s[18:19] offset:0
	v_fmac_f32_e32 v125, v124, v61
	global_store_dword v0, v125, s[18:19] offset:-2048
	v_fmac_f32_e32 v126, v125, v62
	global_store_dword v0, v126, s[18:19] offset:-4096
	v_fmac_f32_e32 v127, v126, v63
	s_add_u32 s18, s14, 0xf000
	s_addc_u32 s19, s15, 0
	global_store_dword v0, v127, s[18:19] offset:2048
	v_fmac_f32_e32 v128, v127, v64
	global_store_dword v0, v128, s[18:19] offset:0
	v_fmac_f32_e32 v129, v128, v65
	global_store_dword v0, v129, s[18:19] offset:-2048
	v_fmac_f32_e32 v130, v129, v66
	global_store_dword v0, v130, s[18:19] offset:-4096
	v_fmac_f32_e32 v131, v130, v67
	s_add_u32 s18, s14, 0xd000
	s_addc_u32 s19, s15, 0
	global_store_dword v0, v131, s[18:19] offset:2048
	v_fmac_f32_e32 v132, v131, v68
	global_store_dword v0, v132, s[18:19] offset:0
	v_fmac_f32_e32 v133, v132, v69
	global_store_dword v0, v133, s[18:19] offset:-2048
	v_fmac_f32_e32 v134, v133, v70
	global_store_dword v0, v134, s[18:19] offset:-4096
	v_fmac_f32_e32 v135, v134, v71
	s_add_u32 s18, s14, 0xb000
	s_addc_u32 s19, s15, 0
	global_store_dword v0, v135, s[18:19] offset:2048
	v_fmac_f32_e32 v136, v135, v72
	global_store_dword v0, v136, s[18:19] offset:0
	v_fmac_f32_e32 v137, v136, v73
	global_store_dword v0, v137, s[18:19] offset:-2048
	v_fmac_f32_e32 v138, v137, v74
	global_store_dword v0, v138, s[18:19] offset:-4096
	v_fmac_f32_e32 v139, v138, v75
	s_add_u32 s18, s14, 0x9000
	s_addc_u32 s19, s15, 0
	global_store_dword v0, v139, s[18:19] offset:2048
	v_fmac_f32_e32 v140, v139, v76
	global_store_dword v0, v140, s[18:19] offset:0
	v_fmac_f32_e32 v141, v140, v77
	global_store_dword v0, v141, s[18:19] offset:-2048
	v_fmac_f32_e32 v142, v141, v78
	global_store_dword v0, v142, s[18:19] offset:-4096
	v_fmac_f32_e32 v143, v142, v79
	s_add_u32 s18, s14, 0x7000
	s_addc_u32 s19, s15, 0
	global_store_dword v0, v143, s[18:19] offset:2048
	v_fmac_f32_e32 v144, v143, v80
	global_store_dword v0, v144, s[18:19] offset:0
	v_fmac_f32_e32 v145, v144, v81
	global_store_dword v0, v145, s[18:19] offset:-2048
	v_fmac_f32_e32 v146, v145, v82
	global_store_dword v0, v146, s[18:19] offset:-4096
	v_fmac_f32_e32 v147, v146, v83
	s_add_u32 s18, s14, 0x5000
	s_addc_u32 s19, s15, 0
	global_store_dword v0, v147, s[18:19] offset:2048
	v_fmac_f32_e32 v148, v147, v84
	global_store_dword v0, v148, s[18:19] offset:0
	v_fmac_f32_e32 v149, v148, v85
	global_store_dword v0, v149, s[18:19] offset:-2048
	v_fmac_f32_e32 v150, v149, v86
	global_store_dword v0, v150, s[18:19] offset:-4096
	v_fmac_f32_e32 v151, v150, v87
	s_add_u32 s18, s14, 0x3000
	s_addc_u32 s19, s15, 0
	global_store_dword v0, v151, s[18:19] offset:2048
	v_fmac_f32_e32 v153, v151, v88
	global_store_dword v0, v153, s[18:19] offset:0
	v_fmac_f32_e32 v154, v153, v89
	global_store_dword v0, v154, s[18:19] offset:-2048
	v_fmac_f32_e32 v155, v154, v90
	global_store_dword v0, v155, s[18:19] offset:-4096
	v_fmac_f32_e32 v156, v155, v91
	s_add_u32 s18, s14, 0x1000
	s_addc_u32 s19, s15, 0
	global_store_dword v0, v156, s[18:19] offset:2048
	v_fmac_f32_e32 v157, v156, v92
	global_store_dword v0, v157, s[18:19] offset:0
	v_fmac_f32_e32 v158, v157, v93
	global_store_dword v0, v158, s[18:19] offset:-2048
	v_fmac_f32_e32 v159, v158, v94
	global_store_dword v0, v159, s[18:19] offset:-4096
	v_fmac_f32_e32 v160, v159, v95
